# MLP1 and MLP2 phases: workgroups of an XCD group start 0..3 x 512 cycles apart so their LDS-DMA bursts do not hit L2 in lockstep
# speedup vs baseline: 1.0012x; 1.0012x over previous
; DEVI int get_tid512() { int t = threadIdx.x; asm volatile("" : "+v"(t)); return t; }
; DEVI int vhalf() { int t = threadIdx.x >> 8; t = __builtin_amdgcn_readfirstlane(t); return t; }
; DEVI void phase_resid_gemm(const Params& p, const bfu* A, int lda, int nkt, const bfu* wT, int ldb, const float* resid32,
;                            float* ssq_out, float* out32, char* lds) {
;   const int lane = get_tid512() & 63, wid = get_tid512() >> 6, wm = wid >> 2, wn = wid & 3, fr = lane & 15, fq = lane >> 4;
;   bfu* xs = (bfu*)(p.ws + OFF_XN);
;   float* part = (float*)(lds + 131072);
;   int stg = 0;
;   int mt, nt;
;   bool have = tile_map(0, 4, mt, nt);
; DEVI void run_phase(const Params& p, int ph, char* lds, volatile int* nsa_cnt, float* p4s, bool rep) {
;   const int l = ph / PH_PER_LAYER, q = ph % PH_PER_LAYER;
;   char* hl = lds + vhalf() * LDS_HALF;
;   switch (q) {
;     case 0: phase1(p, l, hl); break;
;     case 1: phase2(p, l, lds); break;
;     case 2: phase3a(p, l, hl, rep, nsa_cnt); break;
;     case 3: phase3b(p, l, hl, nsa_cnt); break;
;     case 4: phase4(p, l, lds, p4s); break;
;     case 5: phase_resid_gemm(p, (const bfu*)(p.ws + OFF_MIX), LDX, 16, (const bfu*)(p.ws + OFF_WOUT), LDX,
;                              (l == 0) ? p.in[0] : nullptr, (float*)(p.ws + OFF_SSQB), nullptr, lds); break;
;     case 6: phase7(p, l, lds); break;
;     case 7: phase_resid_gemm(p, (const bfu*)(p.ws + OFF_HID), LDH, 64, (const bfu*)(p.ws + OFF_WM2), LDH, nullptr,
;                              (float*)(p.ws + OFF_SSQA), (l == 1) ? p.out : nullptr, lds); break;
.LBB0_14:
	s_ashr_i32 s0, s92, 31
	s_lshr_b32 s0, s0, 29
	s_add_i32 s0, s92, s0
	s_ashr_i32 s4, s0, 3
	v_writelane_b32 v242, s4, 43
	s_and_b32 s0, s0, -8
	s_sub_i32 s0, s92, s0
	v_writelane_b32 v242, s5, 44
	v_readfirstlane_b32 s26, v220
	v_writelane_b32 v242, s0, 45
	s_cmp_lt_i32 s0, 4
	s_mov_b64 s[0:1], -1
	s_cbranch_scc1 .LBB0_474
	v_readlane_b32 s0, v242, 45
	s_cmp_lt_i32 s0, 6
	s_mov_b64 s[0:1], -1
	s_cbranch_scc1 .LBB0_224
	v_readlane_b32 s0, v242, 45
	s_cmp_lt_i32 s0, 7
	s_mov_b64 s[0:1], -1
	s_cbranch_scc1 .LBB0_201
	v_readlane_b32 s0, v242, 45
	s_cmp_eq_u32 s0, 7
	s_cbranch_scc0 .LBB0_200
	v_readlane_b32 s0, v244, 59
	v_readlane_b32 s1, v244, 60
	v_mov_b32_e32 v2, v220
	v_mov_b32_e32 v0, v220
	s_andn2_b64 vcc, exec, s[0:1]
	s_cbranch_vccnz .LBB0_200
	v_readlane_b32 s4, v244, 57
	v_readlane_b32 s5, v244, 58
	s_load_dword s4, s[4:5], 0x0
	s_and_b32 s0, s92, -8
	s_cmp_eq_u32 s0, 8
	s_cselect_b32 s1, s89, 0
	s_cselect_b32 s0, s88, 0
	s_waitcnt lgkmcnt(0)
	s_lshr_b32 s52, s4, 3
	v_bfe_u32 v3, v2, 4, 2
	v_and_b32_e32 v2, 15, v2
	v_bfe_u32 v4, v0, 6, 2
	v_ashrrev_i32_e32 v0, 1, v0
	s_movk_i32 s4, 0xff80
	s_cmp_eq_u64 s[0:1], 0
	v_and_or_b32 v179, v0, s4, v2
	v_lshlrev_b32_e32 v0, 2, v3
	s_cselect_b64 s[4:5], -1, 0
	s_cmp_lg_u64 s[0:1], 0
	v_readlane_b32 s11, v242, 34
	v_readlane_b32 s23, v244, 61
	s_mov_b32 s20, 0
	v_lshl_or_b32 v181, v4, 6, v0
	s_cselect_b64 s[46:47], -1, 0
	v_lshl_add_u32 v183, v4, 2, s11
	v_cmp_eq_u32_e64 s[38:39], 0, v3
	v_lshlrev_b32_e32 v184, 4, v179
	s_mov_b32 s56, 0
	v_readlane_b32 s25, v244, 62
	s_mov_b32 s48, s23
	v_readlane_b32 s101, v243, 13
	s_bfe_u32 s101, s101, 0x20004
.Lstag8:
	s_cmp_eq_u32 s101, 0
	s_cbranch_scc1 .Lstag8_done
	s_sleep 8
	s_sub_u32 s101, s101, 1
	s_branch .Lstag8
.Lstag8_done:
	s_branch .LBB0_22
.LBB0_20:
	s_or_b64 exec, exec, s[36:37]
	s_waitcnt lgkmcnt(0)
	s_barrier

; DEVI int get_tid512() { int t = threadIdx.x; asm volatile("" : "+v"(t)); return t; }
; DEVI void phase7(const Params& p, int l, char* lds) {
;   const bfu* hn = (const bfu*)(p.ws + OFF_XN);
;   const bfu* wT = (const bfu*)(p.ws + OFF_WM1);
;   bfu* hid = (bfu*)(p.ws + OFF_HID);
;   const int lane = get_tid512() & 63, wid = get_tid512() >> 6, wm = wid >> 2, wn = wid & 3, fr = lane & 15, fq = lane >> 4;
;   int stg = 0;
;   int mt, nt;
;   bool have = tile_map(0, 16, mt, nt);
.LBB0_201:
	s_andn2_b64 vcc, exec, s[0:1]
	s_cbranch_vccnz .LBB0_223
	v_readlane_b32 s0, v243, 1
	v_readlane_b32 s1, v243, 2
	s_waitcnt lgkmcnt(0)
	v_mov_b32_e32 v2, v220
	v_mov_b32_e32 v0, v220
	s_andn2_b64 vcc, exec, s[0:1]
	s_cbranch_vccnz .LBB0_223
	v_readlane_b32 s0, v244, 57
	v_readlane_b32 s1, v244, 58
	s_load_dword s0, s[0:1], 0x0
	v_and_b32_e32 v179, 15, v2
	v_lshrrev_b32_e32 v2, 2, v2
	v_ashrrev_i32_e32 v3, 8, v0
	v_and_b32_e32 v2, 12, v2
	s_waitcnt lgkmcnt(0)
	s_lshr_b32 s25, s0, 3
	s_movk_i32 s0, 0xc0
	v_lshlrev_b32_e32 v181, 9, v3
	v_and_or_b32 v183, v0, s0, v2
	v_lshl_or_b32 v184, v3, 7, v179
	s_mov_b32 s20, 0
	s_mov_b32 s43, 0
	v_readlane_b32 s30, v243, 4
	v_readlane_b32 s23, v243, 3
	v_readlane_b32 s101, v243, 13
	s_bfe_u32 s101, s101, 0x20004

; DEVI void phase7(const Params& p, int l, char* lds) {
;     ...
;   for (int it = 0; have; ++it) {
;     int mt2 = 0, nt2 = 0;
;     const bool have2 = tile_map(it + 1, 16, mt2, nt2);
;     const int m0 = mt * 256, n0 = nt * 256;
;     const GUnit cur{hn + (long)m0 * LDX, wT + (long)n0 * LDX, LDX, LDX, 16};
;     const GUnit nxt{hn + (long)mt2 * 256 * LDX, wT + (long)nt2 * 256 * LDX, LDX, LDX, 16};
;     const float* rsS = stage_rstd((const float*)(p.ws + OFF_SSQB), m0, it, lds);
;     f32x4 acc[4][8];
;     zero_acc8(acc);
;     gemm16s(acc, cur, nxt, have2, it == 0, stg, (bfu*)lds);
;     mt = mt2; nt = nt2; have = have2;
.Lstag7_done:
	s_branch .LBB0_205
.LBB0_204:
	s_setprio 0
	s_cmp_eq_u32 s100, 0
	s_cbranch_scc1 .Lp7_released
	v_readlane_b32 vcc_lo, v242, 28
	v_readlane_b32 vcc_hi, v242, 29
